# baseline (speedup 1.0000x reference)
; __device__ __forceinline__ void attn_load_kv(KVRegs& R, const bf16* Z, const bf16* KC, const bf16* VC, const float* sinks, int idx, int kvh, int tid) {
;     const bool sample = idx >= 256; const int c = idx & 31; const int row0 = idx * 64;
;     const int jmin = sample ? 0 : (c >= 2 ? 0 : 2 - c);
;     const int kr = tid >> 3, d0 = (tid & 7) * 8;
;     const v4u z = {0u, 0u, 0u, 0u};
;     R.k0 = z; R.k1 = z; R.k2 = z; R.v0 = z; R.v1 = z; R.v2 = z;
;     if (sample) {
;         const size_t off = ((size_t)((idx - 256) * 128 + kr)) * 256 + kvh * 64 + d0;
;         R.k0 = *(const v4u*)(KC + off); R.v0 = *(const v4u*)(VC + off); R.k1 = *(const v4u*)(KC + off + 64 * 256); R.v1 = *(const v4u*)(VC + off + 64 * 256);
;     } else {
;         const bf16* zr = Z + (size_t)(row0 - 128 + kr) * DIN + kvh * 64 + d0;
;         if (jmin <= 0) { R.k0 = *(const v4u*)(zr + 2048); R.v0 = *(const v4u*)(zr + 2304); }
;         if (jmin <= 1) { R.k1 = *(const v4u*)(zr + (size_t)64 * DIN + 2048); R.v1 = *(const v4u*)(zr + (size_t)64 * DIN + 2304); }
;     }
;     { const bf16* zr = Z + (size_t)(row0 + kr) * DIN + kvh * 64 + d0; R.k2 = *(const v4u*)(zr + 2048); R.v2 = *(const v4u*)(zr + 2304); }
;     { const int wid = tid >> 6, lane = tid & 63, g = wid >> 1, qh = wid & 1, r = lane & 31, h = lane >> 5;
;       const bf16* qp = Z + (size_t)(row0 + qh * 32 + r) * DIN + 1024 + (kvh * 4 + g) * 64 + 8 * h;
;       R.q0 = *(const bf16x8*)qp; R.q1 = *(const bf16x8*)(qp + 16); R.q2 = *(const bf16x8*)(qp + 32); R.q3 = *(const bf16x8*)(qp + 48); R.sink = sinks[kvh * 4 + g]; }
; }
; __device__ __forceinline__ void attn_units(LAS unsigned char* lds, const bf16* Z, const bf16* KC, const bf16* VC, const float* sinks, bf16* MIXIN, int bx, int G, int tid, int wid, int lane) {
;     ...
;         constexpr float SC = 0.125f * 1.44269504089f;
;         float m2 = sink * 1.44269504089f;
; #pragma unroll
;         for (int kt = 0; kt < 6; ++kt) if ((kt >> 1) >= jmin) {
; #pragma unroll
;             for (int i = 0; i < 16; ++i) m2 = fmaxf(m2, st[kt][i] * SC);
;         }
;         m2 = fmaxf(m2, __shfl_xor(m2, 32));
.LBB0_52:
	s_and_b64 s[30:31], s[18:19], exec
	s_cselect_b32 s30, 64, 0
	v_ashrrev_i32_e32 v160, 7, v180
	s_waitcnt lgkmcnt(0)
	s_add_u32 s28, s28, s30
	v_lshl_add_u32 v2, s13, 2, v160
	v_and_b32_e32 v11, 31, v180
	v_lshrrev_b32_e32 v0, 1, v180
	s_addc_u32 s29, s29, 0
	v_ashrrev_i32_e32 v3, 31, v2
	v_and_or_b32 v161, v0, 32, v11
	v_lshl_add_u64 v[4:5], v[2:3], 2, s[28:29]
	v_or_b32_e32 v0, s12, v161
	v_mov_b64_e32 v[8:9], s[8:9]
	global_load_dword v156, v[4:5], off
	v_mad_i64_i32 v[4:5], s[12:13], v0, s75, v[8:9]
	v_lshlrev_b32_e32 v2, 6, v2
	v_lshrrev_b32_e32 v0, 2, v180
	v_ashrrev_i32_e32 v3, 31, v2
	v_and_b32_e32 v10, 8, v0
	v_mad_i64_i32 v[6:7], s[12:13], v6, s75, v[8:9]
	s_lshl_b32 s88, s5, 1
	v_lshl_add_u64 v[2:3], v[2:3], 1, v[4:5]
	v_lshlrev_b32_e32 v0, 1, v10
	v_lshl_add_u64 v[6:7], v[6:7], 0, s[88:89]
	v_mov_b32_e32 v151, v1
	v_lshl_add_u64 v[2:3], v[2:3], 0, v[0:1]
	v_lshl_add_u64 v[6:7], v[6:7], 0, v[150:151]
	global_load_dwordx4 v[138:141], v[2:3], off offset:2144
	global_load_dwordx4 v[142:145], v[2:3], off offset:2112
	global_load_dwordx4 v[146:149], v[2:3], off offset:2080
	s_nop 0
	global_load_dwordx4 v[2:5], v[2:3], off offset:2048
	v_add_co_u32_e32 v6, vcc, s80, v6
	v_lshrrev_b32_e32 v8, 5, v206
	s_nop 0
	v_addc_co_u32_e32 v7, vcc, 0, v7, vcc
	global_load_dwordx4 v[118:121], v[6:7], off offset:512
	global_load_dwordx4 v[114:117], v[6:7], off
	v_and_b32_e32 v12, 64, v204
	s_movk_i32 s12, 0x90
	v_mul_u32_u24_e32 v6, 0x188, v159
	v_lshlrev_b32_e32 v7, 1, v158
	v_xor_b32_e32 v9, 32, v204
	v_lshlrev_b32_e32 v16, 4, v8
	v_add_u32_e32 v12, 64, v12
	v_mul_lo_u32 v0, v158, s12
	v_or_b32_e32 v13, 32, v206
	v_or_b32_e32 v14, 0x60, v206
	v_or_b32_e32 v15, 0xa0, v206
	v_add3_u32 v164, 0, v6, v7
	v_mad_u32_u24 v7, v11, s12, 0
	v_lshlrev_b32_e32 v17, 3, v8
	v_add_u32_e32 v19, 0, v16
	v_cmp_lt_i32_e32 vcc, v9, v12
	s_ashr_i32 s42, s4, 7
	v_readlane_b32 s4, v240, 1
	v_add3_u32 v163, 0, v0, v150
	v_mul_u32_u24_e32 v6, 0x90, v11
	v_lshlrev_b32_e32 v0, 2, v8
	v_mul_u32_u24_e32 v8, 0x90, v13
	v_mul_u32_u24_e32 v14, 0x90, v14
	v_mul_u32_u24_e32 v15, 0x90, v15
	v_mul_u32_u24_e32 v18, 0x188, v11
	v_mul_u32_u24_e32 v13, 0x188, v13
	v_cndmask_b32_e32 v9, v204, v9, vcc
	v_add_u32_e32 v167, v7, v16
	s_lshl_b32 s4, s4, 5
	v_sub_u32_e32 v7, v19, v17
	v_add_u32_e32 v162, 0xffff8000, v158
	s_mov_b32 s5, s2
	v_add_u32_e32 v165, 0x2400, v163
	v_add_u32_e32 v166, 0x4800, v163
	v_lshlrev_b32_e32 v152, 1, v10
	v_lshlrev_b32_e32 v168, 2, v9
	s_lshl_b32 s43, s2, 2
	s_lshl_b32 s44, s3, 2
	v_add_u32_e32 v169, v19, v8
	v_add_u32_e32 v170, v19, v6
	v_add_u32_e32 v171, v19, v14
	v_add_u32_e32 v172, v19, v15
	v_and_or_b32 v154, s4, 32, v11
	v_add_u32_e32 v173, v7, v18
	v_add_u32_e32 v174, v7, v13
	v_lshlrev_b32_e32 v0, 1, v0
	s_waitcnt vmcnt(6)
	v_mov_b32_e32 v151, v156
	s_waitcnt vmcnt(5)
	v_mov_b64_e32 v[134:135], v[138:139]
	s_waitcnt vmcnt(4)
	v_mov_b64_e32 v[130:131], v[142:143]
	s_waitcnt vmcnt(3)
	v_mov_b64_e32 v[126:127], v[146:147]
	s_waitcnt vmcnt(2)
	v_mov_b64_e32 v[124:125], v[4:5]
	v_mov_b64_e32 v[122:123], v[2:3]
	v_mov_b64_e32 v[128:129], v[148:149]
	v_mov_b64_e32 v[132:133], v[144:145]
	v_mov_b64_e32 v[136:137], v[140:141]
	v_lshrrev_b32_e32 v243, 6, v180
	v_mul_u32_u24_e32 v243, 0x1200, v243
	v_add_u32_e32 v243, 0xd000, v243
	v_and_b32_e32 v244, 31, v206
	v_lshrrev_b32_e32 v245, 5, v206
	v_mul_u32_u24_e32 v242, 0x90, v244
	v_lshl_add_u32 v242, v245, 3, v242
	v_add_u32_e32 v242, v242, v243
	v_lshrrev_b32_e32 v246, 3, v206
	v_and_b32_e32 v247, 7, v206
	v_mul_u32_u24_e32 v248, 0x90, v246
	v_lshl_add_u32 v248, v247, 4, v248
	v_add_u32_e32 v243, v248, v243
	v_sub_u32_e32 v244, v246, v244
	v_lshlrev_b32_e32 v244, 12, v244
	v_lshl_add_u32 v244, v247, 4, v244
	v_lshlrev_b32_e32 v245, 3, v245
	v_sub_u32_e32 v244, v244, v245
	v_ashrrev_i32_e32 v245, 31, v244
	s_branch .LBB0_54
.LBB0_53:
	v_mul_f32_e32 v84, 0x3e38aa3b, v18
	v_mul_f32_e32 v85, 0x3e38aa3b, v19
	v_max3_f32 v84, v178, v84, v85
	v_mul_f32_e32 v85, 0x3e38aa3b, v20
	v_mul_f32_e32 v86, 0x3e38aa3b, v21
	v_max3_f32 v84, v84, v85, v86
	v_mul_f32_e32 v85, 0x3e38aa3b, v22
	v_mul_f32_e32 v86, 0x3e38aa3b, v23
	v_max3_f32 v84, v84, v85, v86
	v_mul_f32_e32 v85, 0x3e38aa3b, v24
	v_mul_f32_e32 v86, 0x3e38aa3b, v25
	v_max3_f32 v84, v84, v85, v86
	v_mul_f32_e32 v85, 0x3e38aa3b, v26
	v_mul_f32_e32 v86, 0x3e38aa3b, v27
	v_max3_f32 v84, v84, v85, v86
	v_mul_f32_e32 v85, 0x3e38aa3b, v28
	v_mul_f32_e32 v86, 0x3e38aa3b, v29
	v_max3_f32 v84, v84, v85, v86
	v_mul_f32_e32 v85, 0x3e38aa3b, v30
	v_mul_f32_e32 v86, 0x3e38aa3b, v31
	v_max3_f32 v84, v84, v85, v86
	v_mul_f32_e32 v85, 0x3e38aa3b, v32
	v_mul_f32_e32 v86, 0x3e38aa3b, v33
	v_max3_f32 v84, v84, v85, v86
	v_mul_f32_e32 v85, 0x3e38aa3b, v2
	v_mul_f32_e32 v86, 0x3e38aa3b, v3
	v_max3_f32 v84, v84, v85, v86
	v_mul_f32_e32 v85, 0x3e38aa3b, v4
	v_mul_f32_e32 v86, 0x3e38aa3b, v5
	v_max3_f32 v84, v84, v85, v86
	v_mul_f32_e32 v85, 0x3e38aa3b, v6
	v_mul_f32_e32 v86, 0x3e38aa3b, v7
	v_max3_f32 v84, v84, v85, v86
	v_mul_f32_e32 v85, 0x3e38aa3b, v8
	v_mul_f32_e32 v86, 0x3e38aa3b, v9
	v_max3_f32 v84, v84, v85, v86
	v_mul_f32_e32 v85, 0x3e38aa3b, v10
	v_mul_f32_e32 v86, 0x3e38aa3b, v11
	v_max3_f32 v84, v84, v85, v86
	v_mul_f32_e32 v85, 0x3e38aa3b, v12
	v_mul_f32_e32 v86, 0x3e38aa3b, v13
	v_max3_f32 v84, v84, v85, v86
	v_mul_f32_e32 v85, 0x3e38aa3b, v14
	v_mul_f32_e32 v86, 0x3e38aa3b, v15
	v_max3_f32 v84, v84, v85, v86
	v_mul_f32_e32 v85, 0x3e38aa3b, v16
	v_mul_f32_e32 v86, 0x3e38aa3b, v17
	v_max3_f32 v84, v84, v85, v86
	ds_bpermute_b32 v85, v168, v84
	s_lshl_b32 s5, s4, 6
	s_ashr_i32 s12, s5, 31
	v_mov_b32_e32 v83, s12
	s_and_b32 s4, s43, 12
	s_waitcnt lgkmcnt(0)
; __device__ __forceinline__ void attn_units(LAS unsigned char* lds, const bf16* Z, const bf16* KC, const bf16* VC, const float* sinks, bf16* MIXIN, int bx, int G, int tid, int wid, int lane) {
;     ...
;         float l = 0.f;
; #pragma unroll
;         for (int kt = 0; kt < 6; ++kt) {
;             const bool valid = (kt >> 1) >= jmin;
; #pragma unroll
;             for (int i = 0; i < 16; ++i) { const float p = valid ? __builtin_amdgcn_exp2f(st[kt][i] * SC - m2) : 0.f; st[kt][i] = p; l += p; }
;         }
	v_max_f32_e32 v85, v85, v85
	v_max_f32_e32 v88, v84, v85
	v_fma_f32 v66, v66, s90, -v88
	v_exp_f32_e32 v66, v66
	v_fma_f32 v67, v67, s90, -v88
	v_exp_f32_e32 v67, v67
	v_fma_f32 v68, v68, s90, -v88
	v_exp_f32_e32 v68, v68
	v_fma_f32 v69, v69, s90, -v88
	v_exp_f32_e32 v69, v69
	v_fma_f32 v70, v70, s90, -v88
	v_cndmask_b32_e64 v66, v66, 0, s[36:37]
	v_exp_f32_e32 v70, v70
	v_fma_f32 v71, v71, s90, -v88
	v_add_f32_e32 v84, 0, v66
	v_cndmask_b32_e64 v67, v67, 0, s[36:37]
	v_exp_f32_e32 v71, v71
	v_fma_f32 v72, v72, s90, -v88
	v_add_f32_e32 v84, v67, v84
	v_cndmask_b32_e64 v68, v68, 0, s[36:37]
	v_exp_f32_e32 v72, v72
	v_fma_f32 v73, v73, s90, -v88
	v_add_f32_e32 v84, v68, v84
	v_cndmask_b32_e64 v69, v69, 0, s[36:37]
	v_exp_f32_e32 v73, v73
	v_add_f32_e32 v84, v69, v84
	v_cndmask_b32_e64 v70, v70, 0, s[36:37]
	v_add_f32_e32 v84, v70, v84
	v_cndmask_b32_e64 v71, v71, 0, s[36:37]
	v_add_f32_e32 v85, v71, v84
	v_cndmask_b32_e64 v84, v72, 0, s[36:37]
	v_add_f32_e32 v72, v84, v85
	v_cndmask_b32_e64 v85, v73, 0, s[36:37]
	v_add_f32_e32 v73, v85, v72
	v_fma_f32 v72, v74, s90, -v88
	v_exp_f32_e32 v72, v72
	v_fma_f32 v50, v50, s90, -v88
	v_exp_f32_e32 v50, v50
	v_fma_f32 v51, v51, s90, -v88
	v_cndmask_b32_e64 v72, v72, 0, s[36:37]
	v_add_f32_e32 v74, v72, v73
	v_fma_f32 v73, v75, s90, -v88
	v_exp_f32_e32 v73, v73
	v_exp_f32_e32 v51, v51
	v_fma_f32 v52, v52, s90, -v88
	v_exp_f32_e32 v52, v52
	v_cndmask_b32_e64 v73, v73, 0, s[36:37]
	v_add_f32_e32 v75, v73, v74
	v_fma_f32 v74, v76, s90, -v88
	v_exp_f32_e32 v74, v74
	v_fma_f32 v53, v53, s90, -v88
	v_exp_f32_e32 v53, v53
	v_fma_f32 v54, v54, s90, -v88
	v_cndmask_b32_e64 v74, v74, 0, s[36:37]
	v_add_f32_e32 v76, v74, v75
	v_fma_f32 v75, v77, s90, -v88
	v_exp_f32_e32 v75, v75
	v_cndmask_b32_e64 v50, v50, 0, s[36:37]
	v_exp_f32_e32 v54, v54
	v_fma_f32 v55, v55, s90, -v88
	v_cndmask_b32_e64 v75, v75, 0, s[36:37]
	v_add_f32_e32 v77, v75, v76
	v_fma_f32 v76, v78, s90, -v88
	v_exp_f32_e32 v76, v76
	v_cndmask_b32_e64 v51, v51, 0, s[36:37]
	v_exp_f32_e32 v55, v55
	v_fma_f32 v56, v56, s90, -v88
	v_cndmask_b32_e64 v76, v76, 0, s[36:37]
	v_add_f32_e32 v78, v76, v77
	v_fma_f32 v77, v79, s90, -v88
	v_exp_f32_e32 v77, v77
	v_cndmask_b32_e64 v52, v52, 0, s[36:37]
	v_exp_f32_e32 v56, v56
	v_cndmask_b32_e64 v53, v53, 0, s[36:37]
	v_cndmask_b32_e64 v77, v77, 0, s[36:37]
	v_add_f32_e32 v79, v77, v78
	v_fma_f32 v78, v80, s90, -v88
	v_exp_f32_e32 v78, v78
	v_cndmask_b32_e64 v54, v54, 0, s[36:37]
	v_fma_f32 v34, v34, s90, -v88
	v_exp_f32_e32 v34, v34
	v_cndmask_b32_e64 v78, v78, 0, s[36:37]
	v_add_f32_e32 v80, v78, v79
	v_fma_f32 v79, v81, s90, -v88
	v_exp_f32_e32 v79, v79
	v_fma_f32 v35, v35, s90, -v88
	v_exp_f32_e32 v35, v35
	v_fma_f32 v36, v36, s90, -v88
	v_cndmask_b32_e64 v79, v79, 0, s[36:37]
	v_add_f32_e32 v80, v79, v80
	v_add_f32_e32 v80, v50, v80
	v_add_f32_e32 v80, v51, v80
	v_add_f32_e32 v80, v52, v80
	v_add_f32_e32 v80, v53, v80
	v_add_f32_e32 v81, v54, v80
	v_cndmask_b32_e64 v80, v55, 0, s[36:37]
	v_add_f32_e32 v55, v80, v81
	v_cndmask_b32_e64 v81, v56, 0, s[36:37]
	v_fma_f32 v56, v57, s90, -v88
	v_exp_f32_e32 v56, v56
	v_add_f32_e32 v55, v81, v55
	v_exp_f32_e32 v36, v36
	v_fma_f32 v37, v37, s90, -v88
	v_cndmask_b32_e64 v86, v56, 0, s[36:37]
	v_add_f32_e32 v56, v86, v55
	v_fma_f32 v55, v58, s90, -v88
	v_exp_f32_e32 v55, v55
	v_exp_f32_e32 v37, v37
	v_fma_f32 v38, v38, s90, -v88
	v_cndmask_b32_e64 v34, v34, 0, s[34:35]
	v_cndmask_b32_e64 v55, v55, 0, s[36:37]
	v_add_f32_e32 v57, v55, v56
	v_fma_f32 v56, v59, s90, -v88
	v_exp_f32_e32 v56, v56
	v_exp_f32_e32 v38, v38
	v_fma_f32 v39, v39, s90, -v88
	v_cndmask_b32_e64 v35, v35, 0, s[34:35]
	v_cndmask_b32_e64 v56, v56, 0, s[36:37]
	v_add_f32_e32 v58, v56, v57
	v_fma_f32 v57, v60, s90, -v88
	v_exp_f32_e32 v57, v57
	v_exp_f32_e32 v39, v39
	v_fma_f32 v40, v40, s90, -v88
	v_cndmask_b32_e64 v36, v36, 0, s[34:35]
	v_cndmask_b32_e64 v57, v57, 0, s[36:37]
	v_add_f32_e32 v59, v57, v58
	v_fma_f32 v58, v61, s90, -v88
	v_exp_f32_e32 v58, v58
	v_exp_f32_e32 v40, v40
	v_cndmask_b32_e64 v37, v37, 0, s[34:35]
	v_cndmask_b32_e64 v38, v38, 0, s[34:35]
	v_cndmask_b32_e64 v58, v58, 0, s[36:37]
	v_add_f32_e32 v60, v58, v59
	v_fma_f32 v59, v62, s90, -v88
	v_exp_f32_e32 v59, v59
	v_fma_f32 v18, v18, s90, -v88
	v_exp_f32_e32 v187, v18
	v_fma_f32 v19, v19, s90, -v88
	v_cndmask_b32_e64 v59, v59, 0, s[36:37]
	v_add_f32_e32 v61, v59, v60
	v_fma_f32 v60, v63, s90, -v88
	v_exp_f32_e32 v60, v60
	v_exp_f32_e32 v188, v19
	v_fma_f32 v19, v20, s90, -v88
	v_exp_f32_e32 v189, v19
	v_cndmask_b32_e64 v60, v60, 0, s[36:37]
	v_add_f32_e32 v62, v60, v61
	v_fma_f32 v61, v64, s90, -v88
	v_exp_f32_e32 v61, v61
	v_fma_f32 v19, v21, s90, -v88
	v_exp_f32_e32 v208, v19
	v_fma_f32 v19, v22, s90, -v88
	v_cndmask_b32_e64 v61, v61, 0, s[36:37]
	v_add_f32_e32 v63, v61, v62
	v_fma_f32 v62, v65, s90, -v88
	v_exp_f32_e32 v62, v62
	v_exp_f32_e32 v209, v19
	v_fma_f32 v19, v23, s90, -v88
	v_exp_f32_e32 v210, v19
	v_cndmask_b32_e64 v62, v62, 0, s[36:37]
	v_add_f32_e32 v63, v62, v63
	v_add_f32_e32 v63, v34, v63
	v_add_f32_e32 v63, v35, v63
	v_add_f32_e32 v63, v36, v63
	v_add_f32_e32 v63, v37, v63
	v_add_f32_e32 v64, v38, v63
	v_cndmask_b32_e64 v63, v39, 0, s[34:35]
	v_add_f32_e32 v39, v63, v64
	v_cndmask_b32_e64 v64, v40, 0, s[34:35]
	v_fma_f32 v40, v41, s90, -v88
	v_exp_f32_e32 v40, v40
	v_add_f32_e32 v39, v64, v39
	v_fma_f32 v19, v24, s90, -v88
	v_exp_f32_e32 v212, v19
	v_cndmask_b32_e64 v65, v40, 0, s[34:35]
	v_add_f32_e32 v40, v65, v39
	v_fma_f32 v39, v42, s90, -v88
	v_exp_f32_e32 v39, v39
	v_fma_f32 v19, v25, s90, -v88
	v_exp_f32_e32 v213, v19
	v_fma_f32 v19, v26, s90, -v88
	v_cndmask_b32_e64 v39, v39, 0, s[34:35]
; __device__ __forceinline__ void attn_units(LAS unsigned char* lds, const bf16* Z, const bf16* KC, const bf16* VC, const float* sinks, bf16* MIXIN, int bx, int G, int tid, int wid, int lane) {
;     ...
;         float l = 0.f;
; #pragma unroll
;         for (int kt = 0; kt < 6; ++kt) {
;             const bool valid = (kt >> 1) >= jmin;
; #pragma unroll
;             for (int i = 0; i < 16; ++i) { const float p = valid ? __builtin_amdgcn_exp2f(st[kt][i] * SC - m2) : 0.f; st[kt][i] = p; l += p; }
;         }
;         l += __shfl_xor(l, 32);
;         l += __builtin_amdgcn_exp2f(sink * 1.44269504089f - m2);
	v_add_f32_e32 v41, v39, v40
	v_fma_f32 v40, v43, s90, -v88
	v_exp_f32_e32 v40, v40
	v_fma_f32 v2, v2, s90, -v88
	v_fma_f32 v3, v3, s90, -v88
	s_add_i32 s4, s4, s42
	v_cndmask_b32_e64 v40, v40, 0, s[34:35]
	v_add_f32_e32 v42, v40, v41
	v_fma_f32 v41, v44, s90, -v88
	v_exp_f32_e32 v41, v41
	v_or_b32_e32 v82, s5, v154
	s_lshl_b32 s4, s4, 6
	s_ashr_i32 s5, s4, 31
	v_cndmask_b32_e64 v41, v41, 0, s[34:35]
	v_add_f32_e32 v43, v41, v42
	v_fma_f32 v42, v45, s90, -v88
	v_exp_f32_e32 v42, v42
	v_fma_f32 v45, v47, s90, -v88
	v_exp_f32_e32 v45, v45
	s_add_i32 s43, s43, s44
	v_cndmask_b32_e64 v42, v42, 0, s[34:35]
	v_add_f32_e32 v44, v42, v43
	v_fma_f32 v43, v46, s90, -v88
	v_fma_f32 v46, v48, s90, -v88
	v_sub_f32_e32 v48, v156, v88
	v_exp_f32_e32 v48, v48
	v_exp_f32_e32 v46, v46
	v_exp_f32_e32 v43, v43
	v_cndmask_b32_e64 v45, v45, 0, s[34:35]
	v_cndmask_b32_e64 v94, v48, 0, s[34:35]
	v_sub_f32_e32 v48, v157, v88
	v_exp_f32_e32 v48, v48
	v_cndmask_b32_e64 v91, v46, 0, s[34:35]
	v_fma_f32 v46, v49, s90, -v88
	v_exp_f32_e32 v46, v46
	v_cndmask_b32_e64 v156, v48, 0, s[34:35]
	v_sub_f32_e32 v48, v148, v88
	v_exp_f32_e32 v48, v48
	v_cndmask_b32_e64 v43, v43, 0, s[34:35]
	v_add_f32_e32 v44, v43, v44
	v_add_f32_e32 v44, v45, v44
	v_cndmask_b32_e64 v148, v48, 0, s[34:35]
	v_sub_f32_e32 v48, v149, v88
	v_exp_f32_e32 v48, v48
	v_add_f32_e32 v44, v91, v44
	v_cndmask_b32_e64 v96, v46, 0, s[34:35]
	v_add_f32_e32 v46, v96, v44
	v_sub_f32_e32 v44, v175, v88
	v_exp_f32_e32 v44, v44
	v_cndmask_b32_e64 v149, v48, 0, s[34:35]
	v_sub_f32_e32 v48, v146, v88
	v_exp_f32_e32 v48, v48
	v_cndmask_b32_e64 v44, v44, 0, s[34:35]
	v_add_f32_e32 v47, v44, v46
	v_sub_f32_e32 v46, v176, v88
	v_cndmask_b32_e64 v176, v48, 0, s[34:35]
	v_sub_f32_e32 v48, v147, v88
	v_exp_f32_e32 v48, v48
	v_exp_f32_e32 v46, v46
	v_exp_f32_e32 v157, v19
	v_fma_f32 v19, v27, s90, -v88
	v_cndmask_b32_e64 v182, v48, 0, s[34:35]
	v_sub_f32_e32 v48, v144, v88
	v_exp_f32_e32 v48, v48
	v_cndmask_b32_e64 v46, v46, 0, s[34:35]
	v_add_f32_e32 v47, v46, v47
	v_add_f32_e32 v47, v94, v47
	v_cndmask_b32_e64 v146, v48, 0, s[34:35]
	v_sub_f32_e32 v48, v145, v88
	v_exp_f32_e32 v48, v48
	v_add_f32_e32 v47, v156, v47
	v_add_f32_e32 v47, v148, v47
	v_add_f32_e32 v47, v149, v47
	v_cndmask_b32_e64 v147, v48, 0, s[34:35]
	v_sub_f32_e32 v48, v142, v88
	v_exp_f32_e32 v48, v48
	v_add_f32_e32 v47, v176, v47
	v_add_f32_e32 v47, v182, v47
	v_add_f32_e32 v47, v146, v47
	v_cndmask_b32_e64 v181, v48, 0, s[34:35]
	v_sub_f32_e32 v48, v143, v88
	v_exp_f32_e32 v48, v48
	v_add_f32_e32 v47, v147, v47
	v_add_f32_e32 v47, v181, v47
	v_exp_f32_e32 v175, v19
	v_cndmask_b32_e64 v186, v48, 0, s[34:35]
	v_sub_f32_e32 v48, v140, v88
	v_exp_f32_e32 v48, v48
	v_add_f32_e32 v47, v186, v47
	v_fma_f32 v19, v28, s90, -v88
	v_exp_f32_e32 v177, v19
	v_cndmask_b32_e64 v207, v48, 0, s[34:35]
	v_sub_f32_e32 v48, v141, v88
	v_exp_f32_e32 v48, v48
	v_add_f32_e32 v47, v207, v47
	v_fma_f32 v19, v29, s90, -v88
	v_exp_f32_e32 v178, v19
	v_cndmask_b32_e64 v211, v48, 0, s[34:35]
	v_sub_f32_e32 v48, v138, v88
	v_exp_f32_e32 v48, v48
	v_add_f32_e32 v47, v211, v47
	v_fma_f32 v19, v30, s90, -v88
	v_exp_f32_e32 v179, v19
	v_cndmask_b32_e64 v214, v48, 0, s[34:35]
	v_sub_f32_e32 v48, v139, v88
	v_exp_f32_e32 v48, v48
	v_add_f32_e32 v47, v214, v47
	v_fma_f32 v19, v31, s90, -v88
	v_exp_f32_e32 v183, v19
	v_cndmask_b32_e64 v215, v48, 0, s[34:35]
	v_add_f32_e32 v47, v215, v47
	v_add_f32_e32 v18, v187, v47
	v_add_f32_e32 v18, v188, v18
	v_add_f32_e32 v18, v189, v18
	v_add_f32_e32 v18, v208, v18
	v_add_f32_e32 v18, v209, v18
	v_add_f32_e32 v18, v210, v18
	v_add_f32_e32 v18, v212, v18
	v_add_f32_e32 v18, v213, v18
	v_add_f32_e32 v18, v157, v18
	v_add_f32_e32 v18, v175, v18
	v_fma_f32 v19, v32, s90, -v88
	v_add_f32_e32 v18, v177, v18
	v_exp_f32_e32 v184, v19
	v_fma_f32 v19, v33, s90, -v88
	v_add_f32_e32 v18, v178, v18
	v_exp_f32_e32 v185, v19
	v_add_f32_e32 v18, v179, v18
	v_exp_f32_e32 v138, v2
	v_add_f32_e32 v18, v183, v18
	v_exp_f32_e32 v139, v3
	v_fma_f32 v3, v4, s90, -v88
	v_add_f32_e32 v18, v184, v18
	v_exp_f32_e32 v140, v3
	v_fma_f32 v3, v5, s90, -v88
	v_add_f32_e32 v18, v185, v18
	v_exp_f32_e32 v141, v3
	v_fma_f32 v3, v6, s90, -v88
	v_add_f32_e32 v2, v138, v18
	v_exp_f32_e32 v142, v3
	v_fma_f32 v3, v7, s90, -v88
	v_add_f32_e32 v2, v139, v2
	v_exp_f32_e32 v143, v3
	v_fma_f32 v3, v8, s90, -v88
	v_add_f32_e32 v2, v140, v2
	v_exp_f32_e32 v144, v3
	v_fma_f32 v3, v9, s90, -v88
	v_add_f32_e32 v2, v141, v2
	v_exp_f32_e32 v145, v3
	v_fma_f32 v3, v10, s90, -v88
	v_add_f32_e32 v2, v142, v2
	v_exp_f32_e32 v49, v3
	v_fma_f32 v3, v11, s90, -v88
	v_add_f32_e32 v2, v143, v2
	v_exp_f32_e32 v87, v3
	v_fma_f32 v3, v12, s90, -v88
	v_add_f32_e32 v2, v144, v2
	v_exp_f32_e32 v89, v3
	v_fma_f32 v3, v13, s90, -v88
	v_add_f32_e32 v2, v145, v2
	v_exp_f32_e32 v90, v3
	v_fma_f32 v3, v14, s90, -v88
	v_add_f32_e32 v2, v49, v2
	v_exp_f32_e32 v92, v3
	v_fma_f32 v3, v15, s90, -v88
	v_add_f32_e32 v2, v87, v2
	v_exp_f32_e32 v93, v3
	v_fma_f32 v3, v16, s90, -v88
	v_add_f32_e32 v2, v89, v2
	v_exp_f32_e32 v95, v3
	v_fma_f32 v3, v17, s90, -v88
	v_add_f32_e32 v2, v90, v2
	v_exp_f32_e32 v97, v3
	v_add_f32_e32 v2, v92, v2
	v_add_f32_e32 v2, v93, v2
	v_add_f32_e32 v2, v95, v2
	v_add_f32_e32 v2, v97, v2
	ds_bpermute_b32 v3, v168, v2
	v_sub_f32_e32 v4, v153, v88
	v_add_u32_e32 v88, 0x6800, v173
	v_exp_f32_e32 v47, v4
	v_add_u32_e32 v153, 0x6800, v174
	s_waitcnt lgkmcnt(0)
; __device__ __forceinline__ unsigned cvt_pk_bf16(float lo, float hi) { unsigned r; asm volatile("v_cvt_pk_bf16_f32 %0, %1, %2" : "=v"(r) : "v"(lo), "v"(hi)); return r; }
; #define LAS __attribute__((address_space(3)))
; #define MFMA32(a, b, c) __builtin_amdgcn_mfma_f32_32x32x16_bf16((a), (b), (c), 0, 0, 0)
; __device__ __forceinline__ void attn_units(LAS unsigned char* lds, const bf16* Z, const bf16* KC, const bf16* VC, const float* sinks, bf16* MIXIN, int bx, int G, int tid, int wid, int lane) {
;     ...
;         f32x16 o[2];
; #pragma unroll
;         for (int dt = 0; dt < 2; ++dt)
; #pragma unroll
;             for (int i = 0; i < 16; ++i) o[dt][i] = 0.f;
;         {
;             s16x4 vlo[2][2][2], vhi[2][2][2];
; #pragma unroll
;             for (int s = 0; s < 2; ++s)
; #pragma unroll
;                 for (int dt = 0; dt < 2; ++dt) { const LAS bf16* vp = Vt + (dt * 32 + r) * ATT_VS + 16 * s + 4 * h; vlo[0][s][dt] = *(const LAS s16x4*)vp; vhi[0][s][dt] = *(const LAS s16x4*)(vp + 8); }
; #pragma unroll
;             for (int kt = 0; kt < 6; ++kt) {
;                 if (kt < 5) {
; #pragma unroll
;                     for (int s = 0; s < 2; ++s)
; #pragma unroll
;                         for (int dt = 0; dt < 2; ++dt) { const LAS bf16* vp = Vt + (dt * 32 + r) * ATT_VS + (kt + 1) * 32 + 16 * s + 4 * h; vlo[(kt + 1) & 1][s][dt] = *(const LAS s16x4*)vp; vhi[(kt + 1) & 1][s][dt] = *(const LAS s16x4*)(vp + 8); }
;                 }
; #pragma unroll
;                 for (int s = 0; s < 2; ++s) {
;                     v4u pw; pw.x = pg8::cvt_pk_bf16(st[kt][8 * s + 0], st[kt][8 * s + 1]); pw.y = pg8::cvt_pk_bf16(st[kt][8 * s + 2], st[kt][8 * s + 3]);
;                     pw.z = pg8::cvt_pk_bf16(st[kt][8 * s + 4], st[kt][8 * s + 5]); pw.w = pg8::cvt_pk_bf16(st[kt][8 * s + 6], st[kt][8 * s + 7]);
;                     const bf16x8 pb = __builtin_bit_cast(bf16x8, pw);
; #pragma unroll
;                     for (int dt = 0; dt < 2; ++dt) {
;                         const bf16x8 va = __builtin_shufflevector(vlo[kt & 1][s][dt], vhi[kt & 1][s][dt], 0, 1, 2, 3, 4, 5, 6, 7);
;                         o[dt] = MFMA32(va, pb, o[dt]);
;                     }
;                 }
;             }
;         }
	v_add_f32_e32 v48, v2, v3
	ds_read2_b64 v[2:5], v88 offset0:128 offset1:130
	ds_read2_b64 v[216:219], v88 offset0:132 offset1:134
	ds_read2_b64 v[6:9], v153 offset0:128 offset1:130
	ds_read2_b64 v[220:223], v153 offset0:132 offset1:134
	ds_read2_b64 v[224:227], v88 offset0:136 offset1:138
	ds_read2_b64 v[228:231], v153 offset0:136 offset1:138
	ds_read2_b64 v[232:235], v88 offset0:140 offset1:142
	ds_read2_b64 v[236:239], v153 offset0:140 offset1:142
	v_cvt_pk_bf16_f32 v10, v66, v67
	v_cvt_pk_bf16_f32 v11, v68, v69
	v_cvt_pk_bf16_f32 v12, v70, v71
	v_cvt_pk_bf16_f32 v13, v84, v85
	v_cvt_pk_bf16_f32 v66, v72, v73
	v_cvt_pk_bf16_f32 v67, v74, v75
	v_cvt_pk_bf16_f32 v68, v76, v77
	v_cvt_pk_bf16_f32 v69, v78, v79
	s_waitcnt lgkmcnt(7)
	v_mfma_f32_32x32x16_bf16 v[18:33], v[2:5], v[10:13], 0
	s_waitcnt lgkmcnt(5)
	v_mfma_f32_32x32x16_bf16 v[2:17], v[6:9], v[10:13], 0
	v_mfma_f32_32x32x16_bf16 v[18:33], v[216:219], v[66:69], v[18:33]
	s_waitcnt lgkmcnt(4)
	v_mfma_f32_32x32x16_bf16 v[2:17], v[220:223], v[66:69], v[2:17]
	ds_read2_b64 v[66:69], v88 offset0:144 offset1:146
	ds_read2_b64 v[70:73], v88 offset0:148 offset1:150
	ds_read2_b64 v[74:77], v153 offset0:144 offset1:146
	ds_read2_b64 v[216:219], v153 offset0:148 offset1:150
	v_cvt_pk_bf16_f32 v50, v50, v51
	v_cvt_pk_bf16_f32 v51, v52, v53
	v_cvt_pk_bf16_f32 v52, v54, v80
	v_cvt_pk_bf16_f32 v53, v81, v86
	s_waitcnt lgkmcnt(7)
	v_mfma_f32_32x32x16_bf16 v[18:33], v[224:227], v[50:53], v[18:33]
	s_waitcnt lgkmcnt(6)
	v_mfma_f32_32x32x16_bf16 v[2:17], v[228:231], v[50:53], v[2:17]
	v_cvt_pk_bf16_f32 v50, v55, v56
	v_cvt_pk_bf16_f32 v51, v57, v58
	v_cvt_pk_bf16_f32 v52, v59, v60
	v_cvt_pk_bf16_f32 v53, v61, v62
	s_waitcnt lgkmcnt(5)
	v_mfma_f32_32x32x16_bf16 v[18:33], v[232:235], v[50:53], v[18:33]
	s_waitcnt lgkmcnt(4)
	v_mfma_f32_32x32x16_bf16 v[2:17], v[236:239], v[50:53], v[2:17]
	ds_read2_b64 v[50:53], v88 offset0:152 offset1:154
	ds_read2_b64 v[54:57], v88 offset0:156 offset1:158
	ds_read2_b64 v[58:61], v153 offset0:152 offset1:154
	ds_read2_b64 v[78:81], v153 offset0:156 offset1:158
	v_cvt_pk_bf16_f32 v34, v34, v35
	v_cvt_pk_bf16_f32 v35, v36, v37
	v_cvt_pk_bf16_f32 v36, v38, v63
	v_cvt_pk_bf16_f32 v37, v64, v65
	s_waitcnt lgkmcnt(7)
	v_mfma_f32_32x32x16_bf16 v[18:33], v[66:69], v[34:37], v[18:33]
	s_waitcnt lgkmcnt(5)
	v_mfma_f32_32x32x16_bf16 v[2:17], v[74:77], v[34:37], v[2:17]
	v_cvt_pk_bf16_f32 v34, v39, v40
	v_cvt_pk_bf16_f32 v35, v41, v42
	v_cvt_pk_bf16_f32 v36, v43, v45
	v_cvt_pk_bf16_f32 v37, v91, v96
	s_nop 0
	v_mfma_f32_32x32x16_bf16 v[18:33], v[70:73], v[34:37], v[18:33]
	s_waitcnt lgkmcnt(4)
	v_mfma_f32_32x32x16_bf16 v[2:17], v[216:219], v[34:37], v[2:17]
	ds_read2_b64 v[34:37], v88 offset0:160 offset1:162
	ds_read2_b64 v[38:41], v88 offset0:164 offset1:166
	ds_read2_b64 v[62:65], v153 offset0:160 offset1:162
	ds_read2_b64 v[66:69], v153 offset0:164 offset1:166
	v_cvt_pk_bf16_f32 v42, v44, v46
	v_cvt_pk_bf16_f32 v43, v94, v156
	v_cvt_pk_bf16_f32 v44, v148, v149
	v_cvt_pk_bf16_f32 v45, v176, v182
	s_waitcnt vmcnt(0)
	v_mov_b32_e32 v156, v151
	s_waitcnt lgkmcnt(7)
	v_mfma_f32_32x32x16_bf16 v[18:33], v[50:53], v[42:45], v[18:33]
	s_waitcnt lgkmcnt(5)
	v_mfma_f32_32x32x16_bf16 v[2:17], v[58:61], v[42:45], v[2:17]
	v_cvt_pk_bf16_f32 v42, v146, v147
	v_cvt_pk_bf16_f32 v43, v181, v186
	v_cvt_pk_bf16_f32 v44, v207, v211
	v_cvt_pk_bf16_f32 v45, v214, v215
	v_mov_b64_e32 v[148:149], v[128:129]
	v_mov_b64_e32 v[146:147], v[126:127]
	v_mfma_f32_32x32x16_bf16 v[18:33], v[54:57], v[42:45], v[18:33]
	s_waitcnt lgkmcnt(4)
	v_mfma_f32_32x32x16_bf16 v[2:17], v[78:81], v[42:45], v[2:17]
	ds_read2_b64 v[42:45], v88 offset0:168 offset1:170
	ds_read2_b64 v[50:53], v88 offset0:172 offset1:174
	ds_read2_b64 v[54:57], v153 offset0:168 offset1:170
	ds_read2_b64 v[58:61], v153 offset0:172 offset1:174
	v_cvt_pk_bf16_f32 v70, v187, v188
	v_cvt_pk_bf16_f32 v71, v189, v208
	v_cvt_pk_bf16_f32 v72, v209, v210
	v_cvt_pk_bf16_f32 v73, v212, v213
	s_waitcnt lgkmcnt(7)
	v_mfma_f32_32x32x16_bf16 v[18:33], v[34:37], v[70:73], v[18:33]
	v_cvt_pk_bf16_f32 v34, v157, v175
	v_cvt_pk_bf16_f32 v35, v177, v178
	v_cvt_pk_bf16_f32 v36, v179, v183
	v_cvt_pk_bf16_f32 v37, v184, v185
	s_waitcnt lgkmcnt(5)
; __device__ __forceinline__ unsigned cvt_pk_bf16(float lo, float hi) { unsigned r; asm volatile("v_cvt_pk_bf16_f32 %0, %1, %2" : "=v"(r) : "v"(lo), "v"(hi)); return r; }
; __device__ __forceinline__ void attn_units(LAS unsigned char* lds, const bf16* Z, const bf16* KC, const bf16* VC, const float* sinks, bf16* MIXIN, int bx, int G, int tid, int wid, int lane) {
;     ...
;         const float inv = 1.0f / l;
;         bf16* orow = MIXIN + qrow * DM + 1024 + head * 64;
; #pragma unroll
;         for (int dt = 0; dt < 2; ++dt)
; #pragma unroll
;             for (int g4 = 0; g4 < 4; ++g4) { v2u w; w.x = pg8::cvt_pk_bf16(o[dt][4 * g4] * inv, o[dt][4 * g4 + 1] * inv); w.y = pg8::cvt_pk_bf16(o[dt][4 * g4 + 2] * inv, o[dt][4 * g4 + 3] * inv);
;                 *(v2u*)(orow + dt * 32 + 8 * g4 + 4 * h) = w; }
;         __syncthreads();
	v_mfma_f32_32x32x16_bf16 v[2:17], v[62:65], v[70:73], v[2:17]
	v_mfma_f32_32x32x16_bf16 v[18:33], v[38:41], v[34:37], v[18:33]
	s_waitcnt lgkmcnt(4)
	v_mfma_f32_32x32x16_bf16 v[2:17], v[66:69], v[34:37], v[2:17]
	v_cvt_pk_bf16_f32 v34, v138, v139
	v_cvt_pk_bf16_f32 v35, v140, v141
	v_cvt_pk_bf16_f32 v36, v142, v143
	v_cvt_pk_bf16_f32 v37, v144, v145
	v_mov_b64_e32 v[144:145], v[132:133]
	v_mov_b64_e32 v[140:141], v[136:137]
	v_mov_b64_e32 v[142:143], v[130:131]
	s_waitcnt lgkmcnt(3)
	v_mfma_f32_32x32x16_bf16 v[18:33], v[42:45], v[34:37], v[18:33]
	v_mov_b64_e32 v[138:139], v[134:135]
	s_waitcnt lgkmcnt(1)
	v_mfma_f32_32x32x16_bf16 v[2:17], v[54:57], v[34:37], v[2:17]
	v_cvt_pk_bf16_f32 v34, v49, v87
	v_cvt_pk_bf16_f32 v35, v89, v90
	v_cvt_pk_bf16_f32 v36, v92, v93
	v_cvt_pk_bf16_f32 v37, v95, v97
	s_nop 0
	v_mfma_f32_32x32x16_bf16 v[18:33], v[50:53], v[34:37], v[18:33]
	s_waitcnt lgkmcnt(0)
	v_mfma_f32_32x32x16_bf16 v[2:17], v[58:61], v[34:37], v[2:17]
	v_add_f32_e32 v34, v47, v48
	v_div_scale_f32 v35, s[12:13], v34, v34, 1.0
	v_rcp_f32_e32 v36, v35
	s_nop 0
	v_fma_f32 v37, -v35, v36, 1.0
	v_fmac_f32_e32 v36, v37, v36
	v_div_scale_f32 v37, vcc, 1.0, v34, 1.0
	v_mul_f32_e32 v38, v37, v36
	v_fma_f32 v39, -v35, v38, v37
	v_fmac_f32_e32 v38, v39, v36
	v_fma_f32 v35, -v35, v38, v37
	v_div_fmas_f32 v35, v35, v36, v38
	v_div_fixup_f32 v36, v35, v34, 1.0
	v_lshlrev_b64 v[34:35], 12, v[82:83]
	v_lshl_add_u64 v[34:35], s[16:17], 0, v[34:35]
	v_mul_f32_e32 v18, v18, v36
	v_mul_f32_e32 v19, v19, v36
	v_lshl_add_u64 v[34:35], s[4:5], 1, v[34:35]
	v_cvt_pk_bf16_f32 v18, v18, v19
	v_mul_f32_e32 v19, v20, v36
	v_lshl_add_u64 v[34:35], v[34:35], 0, v[0:1]
	v_mul_f32_e32 v20, v21, v36
	v_cvt_pk_bf16_f32 v19, v19, v20
	ds_write_b64 v242, v[18:19]
	v_mul_f32_e32 v18, v22, v36
	v_mul_f32_e32 v19, v23, v36
	v_cvt_pk_bf16_f32 v18, v18, v19
	v_mul_f32_e32 v19, v24, v36
	v_mul_f32_e32 v20, v25, v36
	v_cvt_pk_bf16_f32 v19, v19, v20
	ds_write_b64 v242, v[18:19] offset:16
	v_mul_f32_e32 v18, v26, v36
	v_mul_f32_e32 v19, v27, v36
	v_cvt_pk_bf16_f32 v18, v18, v19
	v_mul_f32_e32 v19, v28, v36
	v_mul_f32_e32 v20, v29, v36
	v_cvt_pk_bf16_f32 v19, v19, v20
	ds_write_b64 v242, v[18:19] offset:32
	v_mul_f32_e32 v18, v30, v36
	v_mul_f32_e32 v19, v31, v36
	v_cvt_pk_bf16_f32 v18, v18, v19
	v_mul_f32_e32 v19, v32, v36
	v_mul_f32_e32 v2, v2, v36
	v_mul_f32_e32 v3, v3, v36
	v_mul_f32_e32 v20, v33, v36
	v_cvt_pk_bf16_f32 v19, v19, v20
	ds_write_b64 v242, v[18:19] offset:48
	v_cvt_pk_bf16_f32 v2, v2, v3
	v_mul_f32_e32 v3, v4, v36
	v_mul_f32_e32 v4, v5, v36
	v_cvt_pk_bf16_f32 v3, v3, v4
	ds_write_b64 v242, v[2:3] offset:64
	v_mul_f32_e32 v2, v6, v36
	v_mul_f32_e32 v3, v7, v36
	v_cvt_pk_bf16_f32 v2, v2, v3
	v_mul_f32_e32 v3, v8, v36
	v_mul_f32_e32 v4, v9, v36
	v_cvt_pk_bf16_f32 v3, v3, v4
	ds_write_b64 v242, v[2:3] offset:80
	v_mul_f32_e32 v2, v10, v36
	v_mul_f32_e32 v3, v11, v36
	v_cvt_pk_bf16_f32 v2, v2, v3
	v_mul_f32_e32 v3, v12, v36
	v_mul_f32_e32 v4, v13, v36
	v_cvt_pk_bf16_f32 v3, v3, v4
	ds_write_b64 v242, v[2:3] offset:96
	v_mul_f32_e32 v2, v14, v36
	v_mul_f32_e32 v3, v15, v36
	v_cvt_pk_bf16_f32 v2, v2, v3
	v_mul_f32_e32 v3, v16, v36
	v_mul_f32_e32 v4, v17, v36
	v_cvt_pk_bf16_f32 v3, v3, v4
	ds_write_b64 v242, v[2:3] offset:112
	v_lshl_add_u64 v[246:247], v[34:35], 0, v[244:245]
	ds_read_b128 v[248:251], v243
	ds_read_b128 v[252:255], v243 offset:1152
	s_waitcnt lgkmcnt(1)
	global_store_dwordx4 v[246:247], v[248:251], off offset:2048
	v_add_co_u32_e32 v246, vcc, 0x8000, v246
	s_nop 1
	v_addc_co_u32_e32 v247, vcc, 0, v247, vcc
	ds_read_b128 v[248:251], v243 offset:2304
	s_waitcnt lgkmcnt(1)
	global_store_dwordx4 v[246:247], v[252:255], off offset:2048
	v_add_co_u32_e32 v246, vcc, 0x8000, v246
	s_nop 1
	v_addc_co_u32_e32 v247, vcc, 0, v247, vcc
	ds_read_b128 v[252:255], v243 offset:3456
	s_waitcnt lgkmcnt(1)
	global_store_dwordx4 v[246:247], v[248:251], off offset:2048
	v_add_co_u32_e32 v246, vcc, 0x8000, v246
	s_nop 1
	v_addc_co_u32_e32 v247, vcc, 0, v247, vcc
	s_waitcnt lgkmcnt(0)
	global_store_dwordx4 v[246:247], v[252:255], off offset:2048
	v_mov_b64_e32 v[2:3], v[122:123]
	s_andn2_b64 vcc, exec, s[30:31]
	s_mov_b32 s5, s45
	v_mov_b64_e32 v[4:5], v[124:125]
	s_barrier
	s_cbranch_vccz .LBB0_74
